# G1 MFMA segment rotated across the barrier: the last fragment group's 8 MFMAs issue at the start of the next K-step behind its first LDS reads (registers start at zero, flushed after the loop)
# baseline (speedup 1.0000x reference)
; __device__ __forceinline__ bool tile_at(int it, int MT, int NTn, int& mt, int& nt) {
;   const int G = gridDim.x;
;   const int nx = (G % 8 == 0) ? 8 : 1;
;   const int x = blockIdx.x % nx, j = blockIdx.x / nx, nloc = G / nx;
;   const int ch = x + nx * it;
;   const int q = ch * nloc + j;
;   if (q >= MT * NTn) return false;
;   const int gs = 8 * NTn;
;   const int g = q / gs, rem = q - g * gs;
;   const int gsz = min(8, MT - g * 8);
;   nt = rem / gsz;
;   mt = g * 8 + (rem - nt * gsz);
;   return true;
; }
; __device__ __forceinline__ void phase_gemm_in(const Params& p, char* smem) {
;     ...
;   for (int it = 0; it < iters; ++it) {
;     int mt, nt;
;     if (!tile_at(it, MT, NTn, mt, nt)) break;
;     f32x4 acc[8][4];
; #pragma unroll
;     for (int i = 0; i < 8; ++i)
; #pragma unroll
;       for (int j = 0; j < 4; ++j) acc[i][j] = (f32x4){0.f, 0.f, 0.f, 0.f};
;     gemm_core_big(H + (size_t)mt * 256 * 1024, 1024, W + (size_t)nt * 128 * 1024, 1024, 1024, acc, smem);
.LBB0_709:
	s_lshl_b32 s12, s23, s24
	s_add_i32 s12, s12, s22
	s_mul_i32 s14, s12, s16
	s_add_i32 s14, s14, s25
	s_cmpk_gt_i32 s14, 0x11c5
	s_mov_b64 s[12:13], -1
	s_cbranch_scc1 .LBB0_708
	s_mul_hi_i32 s12, s14, 0xea0ea0eb
	s_add_i32 s12, s12, s14
	s_lshr_b32 s13, s12, 31
	s_ashr_i32 s12, s12, 9
	s_add_i32 s12, s12, s13
	s_lshl_b32 s13, s12, 3
	s_sub_i32 s15, 0x41, s13
	s_min_u32 s15, s15, 8
	v_cvt_f32_ubyte0_e32 v0, s15
	v_rcp_iflag_f32_e32 v0, v0
	s_sub_i32 s26, 0, s15
	s_mulk_i32 s12, 0xfdd0
	s_add_i32 s12, s12, s14
	v_mul_f32_e32 v0, 0x4f7ffffe, v0
	v_cvt_u32_f32_e32 v0, v0
	s_abs_i32 s18, s12
	s_ashr_i32 s14, s12, 31
	v_readlane_b32 s0, v241, 11
	v_readfirstlane_b32 s27, v0
	s_mul_i32 s26, s26, s27
	s_mul_hi_u32 s26, s27, s26
	s_add_i32 s27, s27, s26
	s_mul_hi_u32 s27, s18, s27
	s_mul_i32 s26, s27, s15
	s_sub_i32 s18, s18, s26
	s_add_i32 s28, s27, 1
	s_sub_i32 s29, s18, s15
	s_cmp_ge_u32 s18, s15
	s_cselect_b32 s27, s28, s27
	s_cselect_b32 s18, s29, s18
	s_add_i32 s28, s27, 1
	s_cmp_ge_u32 s18, s15
	s_cselect_b32 s18, s28, s27
	s_xor_b32 s18, s18, s14
	s_sub_i32 s14, s18, s14
	s_add_i32 s12, s12, s13
	s_mul_i32 s13, s14, s15
	s_sub_i32 s12, s12, s13
	s_ashr_i32 s13, s12, 31
	s_lshl_b64 s[28:29], s[12:13], 19
	v_readlane_b32 s1, v241, 12
	s_add_u32 s28, s0, s28
	s_addc_u32 s29, s1, s29
	s_ashr_i32 s15, s14, 31
	v_mov_b32_e32 v8, v178
	s_lshl_b64 s[30:31], s[14:15], 18
	v_readlane_b32 s0, v244, 42
	s_add_u32 s30, s0, s30
	v_ashrrev_i32_e32 v4, 3, v8
	v_readlane_b32 s0, v244, 43
	v_ashrrev_i32_e32 v5, 31, v4
	s_addc_u32 s31, s0, s31
	v_lshlrev_b64 v[6:7], 11, v[4:5]
	v_lshlrev_b32_e32 v2, 4, v8
	v_lshrrev_b32_e32 v5, 4, v8
	v_lshl_add_u64 v[0:1], s[28:29], 0, v[6:7]
	v_and_b32_e32 v2, 0x70, v2
	v_lshl_add_u64 v[6:7], s[30:31], 0, v[6:7]
	v_xor_b32_e32 v10, v5, v8
	v_lshl_add_u64 v[0:1], v[0:1], 0, v[2:3]
	v_bfe_u32 v9, v8, 1, 3
	v_lshl_add_u64 v[132:133], v[6:7], 0, v[2:3]
	v_lshlrev_b32_e32 v2, 4, v10
	v_lshlrev_b32_e32 v7, 7, v8
	v_and_b32_e32 v2, 0x70, v2
	v_bitop3_b32 v5, v5, v9, 3 bitop3:0x6c
	v_bfe_u32 v6, v8, 4, 2
	v_and_b32_e32 v8, 0xffffc780, v7
	v_lshl_or_b32 v2, v4, 7, v2
	v_and_b32_e32 v4, 0x2780, v7
	v_lshlrev_b32_e32 v5, 4, v5
	s_waitcnt vmcnt(8)
	v_or_b32_e32 v140, v4, v5
	v_or_b32_e32 v141, v8, v5
	v_bitop3_b32 v5, v6, v9, 4 bitop3:0x36
	v_lshlrev_b32_e32 v5, 4, v5
	s_waitcnt vmcnt(4)
	v_mov_b32_e32 v28, 0
	s_mov_b32 s26, 1
	v_or_b32_e32 v142, v4, v5
	v_or_b32_e32 v143, v8, v5
	v_mov_b64_e32 v[134:135], v[0:1]
	v_mov_b64_e32 v[136:137], v[132:133]
	v_mov_b32_e32 v29, v28
	v_mov_b32_e32 v30, v28
	v_mov_b32_e32 v31, v28
	v_mov_b32_e32 v4, v28
	v_mov_b32_e32 v5, v28
	v_mov_b32_e32 v6, v28
	v_mov_b32_e32 v7, v28
	v_mov_b32_e32 v8, v28
	v_mov_b32_e32 v9, v28
	v_mov_b32_e32 v10, v28
	v_mov_b32_e32 v11, v28
	v_mov_b32_e32 v12, v28
	v_mov_b32_e32 v13, v28
	v_mov_b32_e32 v14, v28
	v_mov_b32_e32 v15, v28
	v_mov_b32_e32 v16, v28
	v_mov_b32_e32 v17, v28
	v_mov_b32_e32 v18, v28
	v_mov_b32_e32 v19, v28
	v_mov_b32_e32 v20, v28
	v_mov_b32_e32 v21, v28
	v_mov_b32_e32 v22, v28
	v_mov_b32_e32 v23, v28
	v_mov_b32_e32 v24, v28
	v_mov_b32_e32 v25, v28
	v_mov_b32_e32 v26, v28
	v_mov_b32_e32 v27, v28
	v_mov_b32_e32 v32, v28
	v_mov_b32_e32 v33, v28
	v_mov_b32_e32 v34, v28
	v_mov_b32_e32 v35, v28
	v_mov_b32_e32 v36, v28
	v_mov_b32_e32 v37, v28
	v_mov_b32_e32 v38, v28
	v_mov_b32_e32 v39, v28
	v_mov_b32_e32 v40, v28
	v_mov_b32_e32 v41, v28
	v_mov_b32_e32 v42, v28
	v_mov_b32_e32 v43, v28
	v_mov_b32_e32 v44, v28
	v_mov_b32_e32 v45, v28
	v_mov_b32_e32 v46, v28
	v_mov_b32_e32 v47, v28
	v_mov_b32_e32 v48, v28
	v_mov_b32_e32 v49, v28
	v_mov_b32_e32 v50, v28
	v_mov_b32_e32 v51, v28
	v_mov_b32_e32 v52, v28
	v_mov_b32_e32 v53, v28
	v_mov_b32_e32 v54, v28
	v_mov_b32_e32 v55, v28
	v_mov_b32_e32 v56, v28
	v_mov_b32_e32 v57, v28
	v_mov_b32_e32 v58, v28
	v_mov_b32_e32 v59, v28
	v_mov_b32_e32 v60, v28
	v_mov_b32_e32 v61, v28
	v_mov_b32_e32 v62, v28
	v_mov_b32_e32 v63, v28
	v_mov_b32_e32 v64, v28
	v_mov_b32_e32 v65, v28
	v_mov_b32_e32 v66, v28
	v_mov_b32_e32 v67, v28
	v_mov_b32_e32 v68, v28
	v_mov_b32_e32 v69, v28
	v_mov_b32_e32 v70, v28
	v_mov_b32_e32 v71, v28
	v_mov_b32_e32 v72, v28
	v_mov_b32_e32 v73, v28
	v_mov_b32_e32 v74, v28
	v_mov_b32_e32 v75, v28
	v_mov_b32_e32 v76, v28
	v_mov_b32_e32 v77, v28
	v_mov_b32_e32 v78, v28
	v_mov_b32_e32 v79, v28
	v_mov_b32_e32 v80, v28
	v_mov_b32_e32 v81, v28
	v_mov_b32_e32 v82, v28
	v_mov_b32_e32 v83, v28
	v_mov_b32_e32 v84, v28
	v_mov_b32_e32 v85, v28
	v_mov_b32_e32 v86, v28
	v_mov_b32_e32 v87, v28
	v_mov_b32_e32 v88, v28
	v_mov_b32_e32 v89, v28
	v_mov_b32_e32 v90, v28
	v_mov_b32_e32 v91, v28
	v_mov_b32_e32 v92, v28
	v_mov_b32_e32 v93, v28
	v_mov_b32_e32 v94, v28
	v_mov_b32_e32 v95, v28
	v_mov_b32_e32 v96, v28
	v_mov_b32_e32 v97, v28
	v_mov_b32_e32 v98, v28
	v_mov_b32_e32 v99, v28
	v_mov_b32_e32 v100, v28
	v_mov_b32_e32 v101, v28
	v_mov_b32_e32 v102, v28
	v_mov_b32_e32 v103, v28
	v_mov_b32_e32 v104, v28
	v_mov_b32_e32 v105, v28
	v_mov_b32_e32 v106, v28
	v_mov_b32_e32 v107, v28
	v_mov_b32_e32 v108, v28
	v_mov_b32_e32 v109, v28
	v_mov_b32_e32 v110, v28
	v_mov_b32_e32 v111, v28
	v_mov_b32_e32 v112, v28
	v_mov_b32_e32 v113, v28
	v_mov_b32_e32 v114, v28
	v_mov_b32_e32 v115, v28
	v_mov_b32_e32 v116, v28
	v_mov_b32_e32 v117, v28
	v_mov_b32_e32 v118, v28
	v_mov_b32_e32 v119, v28
	v_mov_b32_e32 v120, v28
	v_mov_b32_e32 v121, v28
	v_mov_b32_e32 v122, v28
	v_mov_b32_e32 v123, v28
	v_mov_b32_e32 v124, v28
	v_mov_b32_e32 v125, v28
	v_mov_b32_e32 v126, v28
	v_mov_b32_e32 v127, v28
	v_mov_b32_e32 v128, v28
	v_mov_b32_e32 v129, v28
	v_mov_b32_e32 v130, v28
	v_mov_b32_e32 v131, v28
	s_mov_b32 s0, 0x30000
	s_mov_b32 s1, 0x10000
	s_nop 0
	v_lshrrev_b32_e32 v232, 3, v178
	v_and_b32_e32 v233, 7, v178
	v_bfe_u32 v234, v178, 4, 3
	v_xor_b32_e32 v233, v233, v234
	v_lshrrev_b32_e32 v234, 6, v178
	v_lshlrev_b32_e32 v232, 11, v232
	v_lshl_add_u32 v224, v233, 4, v232
	v_add_u32_e32 v225, 0x10000, v224
	v_add_u32_e32 v226, 0x20000, v224
	v_add_u32_e32 v227, 0x30000, v224
	v_add_u32_e32 v228, 0x40000, v224
	v_add_u32_e32 v229, 0x50000, v224
	v_add_u32_e32 v230, 0x60000, v224
	v_add_u32_e32 v231, 0x70000, v224
	v_readfirstlane_b32 s15, v234
	s_lshl_b32 s15, s15, 10
	v_mov_b32_e32 v172, v28
	v_mov_b32_e32 v173, v28
	v_mov_b32_e32 v174, v28
	v_mov_b32_e32 v175, v28
	v_mov_b32_e32 v188, v28
	v_mov_b32_e32 v189, v28
	v_mov_b32_e32 v190, v28
	v_mov_b32_e32 v191, v28
	v_mov_b32_e32 v200, v28
	v_mov_b32_e32 v201, v28
	v_mov_b32_e32 v202, v28
	v_mov_b32_e32 v203, v28
	v_mov_b32_e32 v204, v28
	v_mov_b32_e32 v205, v28
	v_mov_b32_e32 v206, v28
	v_mov_b32_e32 v207, v28
	v_mov_b32_e32 v208, v28
	v_mov_b32_e32 v209, v28
	v_mov_b32_e32 v210, v28
	v_mov_b32_e32 v211, v28
	v_mov_b32_e32 v212, v28
	v_mov_b32_e32 v213, v28
	v_mov_b32_e32 v214, v28
	v_mov_b32_e32 v215, v28
; __device__ __forceinline__ void gemm_core_big(const bf16_t* __restrict__ A, int lda, const bf16_t* __restrict__ Bt, int ldb,
;                                               int K, f32x4 (&acc)[8][4], char* smem) {
;     ...
;   for (int kt = 0; kt < nk; ++kt) {
;     __syncthreads();
; #pragma unroll
;     for (int i = 0; i < 8; ++i) *(u32x4*)(wA + 32 * i * LDS_STRIDE) = ra[i];
; #pragma unroll
;     for (int i = 0; i < 4; ++i) *(u32x4*)(wB + 32 * i * LDS_STRIDE) = rb[i];
;     __syncthreads();
;     {
;       const int k1 = min(kt + 1, nk - 1) << 6;
; #pragma unroll
;       for (int i = 0; i < 8; ++i) ra[i] = *(const u32x4*)(ap + (size_t)(32 * i) * lda + k1);
; #pragma unroll
;       for (int i = 0; i < 4; ++i) rb[i] = *(const u32x4*)(bp + (size_t)(32 * i) * ldb + k1);
;     }
; #pragma unroll
;     for (int ks = 0; ks < 2; ++ks) {
;       const int fo = ks ? fo1 : fo0;
;       bf16x8 bfr[4];
; #pragma unroll
;       for (int j = 0; j < 4; ++j) bfr[j] = *(const bf16x8*)(cB + j * 16 * LDS_STRIDE + fo);
; #pragma unroll
;       for (int i = 0; i < 8; ++i) {
;         const bf16x8 af = *(const bf16x8*)(cA + i * 16 * LDS_STRIDE + fo);
; #pragma unroll
;         for (int j = 0; j < 4; ++j)
;           acc[i][j] = __builtin_amdgcn_mfma_f32_16x16x32_bf16(bfr[j], af, acc[i][j], 0, 0, 0);
;       }
;     }
.LBB0_711:
	s_setprio 0
	s_barrier
	s_add_i32 m0, s15, 0x8000
	s_nop 0
	global_load_lds_dwordx4 v224, s[30:31]
	s_mov_b32 m0, s15
	s_nop 0
	global_load_lds_dwordx4 v224, s[28:29]
	s_add_i32 m0, s15, 0x1000
	s_nop 0
	global_load_lds_dwordx4 v225, s[28:29]
	s_add_i32 m0, s15, 0x2000
	s_nop 0
	global_load_lds_dwordx4 v226, s[28:29]
	s_add_i32 m0, s15, 0x3000
	s_nop 0
	global_load_lds_dwordx4 v227, s[28:29]
	s_add_i32 m0, s15, 0x4000
	s_nop 0
	global_load_lds_dwordx4 v228, s[28:29]
	s_add_i32 m0, s15, 0x5000
	s_nop 0
	global_load_lds_dwordx4 v229, s[28:29]
	s_add_i32 m0, s15, 0x6000
	s_nop 0
	global_load_lds_dwordx4 v230, s[28:29]
	s_add_i32 m0, s15, 0x7000
	s_nop 0
	global_load_lds_dwordx4 v231, s[28:29]
	s_add_i32 m0, s15, 0x9000
	s_nop 0
	global_load_lds_dwordx4 v225, s[30:31]
	s_add_i32 m0, s15, 0xa000
	s_nop 0
	global_load_lds_dwordx4 v226, s[30:31]
	s_add_i32 m0, s15, 0xb000
	s_nop 0
	global_load_lds_dwordx4 v227, s[30:31]
	s_add_u32 s28, s28, 0x80
	s_addc_u32 s29, s29, 0
	s_add_u32 s30, s30, 0x80
	s_addc_u32 s31, s31, 0
	s_add_i32 s26, s26, 1
	s_lshl_b32 s18, s13, 7
	s_cmp_lg_u32 s26, 17
	s_waitcnt vmcnt(0)
	s_barrier
	ds_read_b128 v[134:137], v140 offset:32768
	ds_read_b128 v[148:151], v141 offset:0
	ds_read_b128 v[144:147], v140 offset:34816
	ds_read_b128 v[156:159], v140 offset:36864
	ds_read_b128 v[160:163], v140 offset:38912
	ds_read_b128 v[152:155], v141 offset:2048
	ds_read_b128 v[216:219], v141 offset:4096
	ds_read_b128 v[220:223], v141 offset:6144
	ds_read_b128 v[164:167], v141 offset:8192
	ds_read_b128 v[168:171], v141 offset:10240
	s_setprio 1
	v_mfma_f32_16x16x32_bf16 v[32:35], v[200:203], v[172:175], v[32:35]
	v_mfma_f32_16x16x32_bf16 v[24:27], v[204:207], v[172:175], v[24:27]
	v_mfma_f32_16x16x32_bf16 v[20:23], v[208:211], v[172:175], v[20:23]
	v_mfma_f32_16x16x32_bf16 v[16:19], v[212:215], v[172:175], v[16:19]
	v_mfma_f32_16x16x32_bf16 v[12:15], v[200:203], v[188:191], v[12:15]
	v_mfma_f32_16x16x32_bf16 v[8:11], v[204:207], v[188:191], v[8:11]
	v_mfma_f32_16x16x32_bf16 v[4:7], v[208:211], v[188:191], v[4:7]
	v_mfma_f32_16x16x32_bf16 v[28:31], v[212:215], v[188:191], v[28:31]
	s_waitcnt lgkmcnt(8)
	v_mfma_f32_16x16x32_bf16 v[128:131], v[134:137], v[148:151], v[128:131]
	s_waitcnt lgkmcnt(7)
	v_mfma_f32_16x16x32_bf16 v[124:127], v[144:147], v[148:151], v[124:127]
	s_waitcnt lgkmcnt(6)
	v_mfma_f32_16x16x32_bf16 v[120:123], v[156:159], v[148:151], v[120:123]
	s_waitcnt lgkmcnt(5)
	v_mfma_f32_16x16x32_bf16 v[116:119], v[160:163], v[148:151], v[116:119]
	s_waitcnt lgkmcnt(4)
	v_mfma_f32_16x16x32_bf16 v[112:115], v[134:137], v[152:155], v[112:115]
	v_mfma_f32_16x16x32_bf16 v[108:111], v[144:147], v[152:155], v[108:111]
	v_mfma_f32_16x16x32_bf16 v[104:107], v[156:159], v[152:155], v[104:107]
	v_mfma_f32_16x16x32_bf16 v[100:103], v[160:163], v[152:155], v[100:103]
	ds_read_b128 v[172:175], v141 offset:12288
	ds_read_b128 v[188:191], v141 offset:14336
	s_waitcnt lgkmcnt(5)
	v_mfma_f32_16x16x32_bf16 v[96:99], v[134:137], v[216:219], v[96:99]
	v_mfma_f32_16x16x32_bf16 v[92:95], v[144:147], v[216:219], v[92:95]
	v_mfma_f32_16x16x32_bf16 v[88:91], v[156:159], v[216:219], v[88:91]
	v_mfma_f32_16x16x32_bf16 v[84:87], v[160:163], v[216:219], v[84:87]
	s_waitcnt lgkmcnt(4)
	v_mfma_f32_16x16x32_bf16 v[80:83], v[134:137], v[220:223], v[80:83]
	v_mfma_f32_16x16x32_bf16 v[76:79], v[144:147], v[220:223], v[76:79]
	v_mfma_f32_16x16x32_bf16 v[72:75], v[156:159], v[220:223], v[72:75]
	v_mfma_f32_16x16x32_bf16 v[68:71], v[160:163], v[220:223], v[68:71]
	ds_read_b128 v[148:151], v143 offset:0
	ds_read_b128 v[152:155], v143 offset:2048
	ds_read_b128 v[200:203], v142 offset:32768
	ds_read_b128 v[204:207], v142 offset:34816
	ds_read_b128 v[208:211], v142 offset:36864
	ds_read_b128 v[212:215], v142 offset:38912
	s_waitcnt lgkmcnt(9)
	v_mfma_f32_16x16x32_bf16 v[64:67], v[134:137], v[164:167], v[64:67]
	v_mfma_f32_16x16x32_bf16 v[60:63], v[144:147], v[164:167], v[60:63]
	v_mfma_f32_16x16x32_bf16 v[56:59], v[156:159], v[164:167], v[56:59]
	v_mfma_f32_16x16x32_bf16 v[52:55], v[160:163], v[164:167], v[52:55]
	s_waitcnt lgkmcnt(8)
	v_mfma_f32_16x16x32_bf16 v[48:51], v[134:137], v[168:171], v[48:51]
	v_mfma_f32_16x16x32_bf16 v[44:47], v[144:147], v[168:171], v[44:47]
	v_mfma_f32_16x16x32_bf16 v[40:43], v[156:159], v[168:171], v[40:43]
	v_mfma_f32_16x16x32_bf16 v[36:39], v[160:163], v[168:171], v[36:39]
	ds_read_b128 v[216:219], v143 offset:4096
	ds_read_b128 v[220:223], v143 offset:6144
	s_waitcnt lgkmcnt(9)
	v_mfma_f32_16x16x32_bf16 v[32:35], v[134:137], v[172:175], v[32:35]
	v_mfma_f32_16x16x32_bf16 v[24:27], v[144:147], v[172:175], v[24:27]
	v_mfma_f32_16x16x32_bf16 v[20:23], v[156:159], v[172:175], v[20:23]
	v_mfma_f32_16x16x32_bf16 v[16:19], v[160:163], v[172:175], v[16:19]
	s_waitcnt lgkmcnt(8)
	v_mfma_f32_16x16x32_bf16 v[12:15], v[134:137], v[188:191], v[12:15]
	v_mfma_f32_16x16x32_bf16 v[8:11], v[144:147], v[188:191], v[8:11]
	v_mfma_f32_16x16x32_bf16 v[4:7], v[156:159], v[188:191], v[4:7]
	v_mfma_f32_16x16x32_bf16 v[28:31], v[160:163], v[188:191], v[28:31]
	ds_read_b128 v[164:167], v143 offset:8192
	ds_read_b128 v[168:171], v143 offset:10240
	s_waitcnt lgkmcnt(7)
	v_mfma_f32_16x16x32_bf16 v[128:131], v[200:203], v[148:151], v[128:131]
	s_waitcnt lgkmcnt(6)
	v_mfma_f32_16x16x32_bf16 v[124:127], v[204:207], v[148:151], v[124:127]
	s_waitcnt lgkmcnt(5)
	v_mfma_f32_16x16x32_bf16 v[120:123], v[208:211], v[148:151], v[120:123]
	s_waitcnt lgkmcnt(4)
; __device__ __forceinline__ unsigned pack2(float a, float b) { return (unsigned)f2bf(a) | ((unsigned)f2bf(b) << 16); }
; __device__ __forceinline__ void gemm_core_big(const bf16_t* __restrict__ A, int lda, const bf16_t* __restrict__ Bt, int ldb,
;                                               int K, f32x4 (&acc)[8][4], char* smem) {
;     ...
;     for (int ks = 0; ks < 2; ++ks) {
;       const int fo = ks ? fo1 : fo0;
;       bf16x8 bfr[4];
; #pragma unroll
;       for (int j = 0; j < 4; ++j) bfr[j] = *(const bf16x8*)(cB + j * 16 * LDS_STRIDE + fo);
; #pragma unroll
;       for (int i = 0; i < 8; ++i) {
;         const bf16x8 af = *(const bf16x8*)(cA + i * 16 * LDS_STRIDE + fo);
; #pragma unroll
;         for (int j = 0; j < 4; ++j)
;           acc[i][j] = __builtin_amdgcn_mfma_f32_16x16x32_bf16(bfr[j], af, acc[i][j], 0, 0, 0);
;       }
;     }
; __device__ __forceinline__ void phase_gemm_in(const Params& p, char* smem) {
;     ...
;     bf16_t* dst; int ldd, ncol0;
;     if (nt < PRE_W / 128) { dst = PRE; ldd = PRE_W; ncol0 = nt * 128; }
;     else { dst = POST; ldd = POST_W; ncol0 = (nt - PRE_W / 128) * 128; }
; #pragma unroll
;     for (int i = 0; i < 8; ++i) {
;       const int m = mt * 256 + wm * 128 + i * 16 + (lane & 15);
; #pragma unroll
;       for (int j = 0; j < 4; ++j) {
;         const int n = ncol0 + wn * 64 + j * 16 + (lane >> 4) * 4;
;         uint2 o;
;         o.x = pack2(acc[i][j][0], acc[i][j][1]);
;         o.y = pack2(acc[i][j][2], acc[i][j][3]);
;         *(uint2*)(dst + (size_t)m * ldd + n) = o;
;       }
;     }
	v_mfma_f32_16x16x32_bf16 v[116:119], v[212:215], v[148:151], v[116:119]
	v_mfma_f32_16x16x32_bf16 v[112:115], v[200:203], v[152:155], v[112:115]
	v_mfma_f32_16x16x32_bf16 v[108:111], v[204:207], v[152:155], v[108:111]
	v_mfma_f32_16x16x32_bf16 v[104:107], v[208:211], v[152:155], v[104:107]
	v_mfma_f32_16x16x32_bf16 v[100:103], v[212:215], v[152:155], v[100:103]
	ds_read_b128 v[172:175], v143 offset:12288
	ds_read_b128 v[188:191], v143 offset:14336
	s_waitcnt lgkmcnt(5)
	v_mfma_f32_16x16x32_bf16 v[96:99], v[200:203], v[216:219], v[96:99]
	v_mfma_f32_16x16x32_bf16 v[92:95], v[204:207], v[216:219], v[92:95]
	v_mfma_f32_16x16x32_bf16 v[88:91], v[208:211], v[216:219], v[88:91]
	v_mfma_f32_16x16x32_bf16 v[84:87], v[212:215], v[216:219], v[84:87]
	s_waitcnt lgkmcnt(4)
	v_mfma_f32_16x16x32_bf16 v[80:83], v[200:203], v[220:223], v[80:83]
	v_mfma_f32_16x16x32_bf16 v[76:79], v[204:207], v[220:223], v[76:79]
	v_mfma_f32_16x16x32_bf16 v[72:75], v[208:211], v[220:223], v[72:75]
	v_mfma_f32_16x16x32_bf16 v[68:71], v[212:215], v[220:223], v[68:71]
	s_waitcnt lgkmcnt(3)
	v_mfma_f32_16x16x32_bf16 v[64:67], v[200:203], v[164:167], v[64:67]
	v_mfma_f32_16x16x32_bf16 v[60:63], v[204:207], v[164:167], v[60:63]
	v_mfma_f32_16x16x32_bf16 v[56:59], v[208:211], v[164:167], v[56:59]
	v_mfma_f32_16x16x32_bf16 v[52:55], v[212:215], v[164:167], v[52:55]
	s_waitcnt lgkmcnt(2)
	v_mfma_f32_16x16x32_bf16 v[48:51], v[200:203], v[168:171], v[48:51]
	v_mfma_f32_16x16x32_bf16 v[44:47], v[204:207], v[168:171], v[44:47]
	v_mfma_f32_16x16x32_bf16 v[40:43], v[208:211], v[168:171], v[40:43]
	v_mfma_f32_16x16x32_bf16 v[36:39], v[212:215], v[168:171], v[36:39]
	s_waitcnt lgkmcnt(0)
	s_cbranch_scc1 .LBB0_711
	v_mfma_f32_16x16x32_bf16 v[32:35], v[200:203], v[172:175], v[32:35]
	v_mfma_f32_16x16x32_bf16 v[24:27], v[204:207], v[172:175], v[24:27]
	v_mfma_f32_16x16x32_bf16 v[20:23], v[208:211], v[172:175], v[20:23]
	v_mfma_f32_16x16x32_bf16 v[16:19], v[212:215], v[172:175], v[16:19]
	v_mfma_f32_16x16x32_bf16 v[12:15], v[200:203], v[188:191], v[12:15]
	v_mfma_f32_16x16x32_bf16 v[8:11], v[204:207], v[188:191], v[8:11]
	v_mfma_f32_16x16x32_bf16 v[4:7], v[208:211], v[188:191], v[4:7]
	v_mfma_f32_16x16x32_bf16 v[28:31], v[212:215], v[188:191], v[28:31]
	s_setprio 0
	s_lshl_b32 s13, s14, 7
	s_add_i32 s15, s13, 0xffffef00
	s_cmp_lt_i32 s14, 34
	s_mov_b32 s14, 0x4100000
	s_cselect_b32 s18, s14, 0xcb20000
	s_movk_i32 s0, 0x1200
	s_cselect_b32 s15, s13, s15
	s_cselect_b32 s14, 0x1100, s0
	v_lshl_add_u32 v2, s12, 8, v138
	s_add_u32 s12, s10, s18
	v_or_b32_e32 v0, s15, v139
	s_addc_u32 s13, s11, 0
	s_lshl_b32 s18, s14, 4
	v_ashrrev_i32_e32 v1, 31, v0
	v_lshlrev_b64 v[0:1], 1, v[0:1]
	v_bfe_u32 v136, v178, 4, 1
	v_mul_u32_u24_e32 v136, 24, v136
	v_add_u32_e32 v0, v0, v136
	v_bfe_u32 v136, v178, 3, 1
	v_lshlrev_b32_e32 v136, 6, v136
	v_add_u32_e32 v0, v0, v136
	v_and_b32_e32 v2, 0xfffffff7, v2
	v_mad_i64_i32 v[132:133], s[26:27], s14, v2, 0
	v_lshl_add_u64 v[132:133], v[132:133], 1, s[12:13]
	v_lshl_add_u64 v[132:133], v[132:133], 0, v[0:1]
	v_lshl_add_u64 v[134:135], v[132:133], 0, s[18:19]
	v_cvt_pk_bf16_f32 v144, v128, v129
	v_cvt_pk_bf16_f32 v146, v124, v125
	v_cvt_pk_bf16_f32 v145, v130, v131
	v_cvt_pk_bf16_f32 v147, v126, v127
	v_cvt_pk_bf16_f32 v148, v120, v121
	v_cvt_pk_bf16_f32 v150, v116, v117
	v_cvt_pk_bf16_f32 v149, v122, v123
	v_cvt_pk_bf16_f32 v151, v118, v119
	v_permlane16_swap_b32_e32 v144, v146
	v_permlane16_swap_b32_e32 v145, v147
	v_permlane16_swap_b32_e32 v148, v150
	v_permlane16_swap_b32_e32 v149, v151
	v_mov_b32_e32 v152, v144
	v_mov_b32_e32 v153, v145
	v_mov_b32_e32 v154, v146
	v_mov_b32_e32 v155, v147
	v_mov_b32_dpp v144, v148 row_ror:8 row_mask:0xf bank_mask:0xc
	v_mov_b32_dpp v145, v149 row_ror:8 row_mask:0xf bank_mask:0xc
	v_mov_b32_dpp v146, v150 row_ror:8 row_mask:0xf bank_mask:0xc
	v_mov_b32_dpp v147, v151 row_ror:8 row_mask:0xf bank_mask:0xc
	v_mov_b32_dpp v148, v152 row_ror:8 row_mask:0xf bank_mask:0x3
	v_mov_b32_dpp v149, v153 row_ror:8 row_mask:0xf bank_mask:0x3
	v_mov_b32_dpp v150, v154 row_ror:8 row_mask:0xf bank_mask:0x3
	v_mov_b32_dpp v151, v155 row_ror:8 row_mask:0xf bank_mask:0x3
	global_store_dwordx4 v[132:133], v[144:147], off nt
	global_store_dwordx4 v[134:135], v[148:151], off nt
	v_or_b32_e32 v172, 0x10, v2
	v_mad_i64_i32 v[168:169], s[26:27], s14, v172, 0
	v_lshl_add_u64 v[168:169], v[168:169], 1, s[12:13]
	v_lshl_add_u64 v[168:169], v[168:169], 0, v[0:1]
	v_lshl_add_u64 v[170:171], v[168:169], 0, s[18:19]
	v_cvt_pk_bf16_f32 v156, v112, v113
	v_cvt_pk_bf16_f32 v158, v108, v109
	v_cvt_pk_bf16_f32 v157, v114, v115
	v_cvt_pk_bf16_f32 v159, v110, v111
	v_cvt_pk_bf16_f32 v160, v104, v105
	v_cvt_pk_bf16_f32 v162, v100, v101
	v_cvt_pk_bf16_f32 v161, v106, v107
	v_cvt_pk_bf16_f32 v163, v102, v103
	v_permlane16_swap_b32_e32 v156, v158
	v_permlane16_swap_b32_e32 v157, v159
	v_permlane16_swap_b32_e32 v160, v162
	v_permlane16_swap_b32_e32 v161, v163
	v_mov_b32_e32 v164, v156
	v_mov_b32_e32 v165, v157
	v_mov_b32_e32 v166, v158
	v_mov_b32_e32 v167, v159
	v_mov_b32_dpp v156, v160 row_ror:8 row_mask:0xf bank_mask:0xc
	v_mov_b32_dpp v157, v161 row_ror:8 row_mask:0xf bank_mask:0xc
	v_mov_b32_dpp v158, v162 row_ror:8 row_mask:0xf bank_mask:0xc
	v_mov_b32_dpp v159, v163 row_ror:8 row_mask:0xf bank_mask:0xc
	v_mov_b32_dpp v160, v164 row_ror:8 row_mask:0xf bank_mask:0x3
	v_mov_b32_dpp v161, v165 row_ror:8 row_mask:0xf bank_mask:0x3
	v_mov_b32_dpp v162, v166 row_ror:8 row_mask:0xf bank_mask:0x3
	v_mov_b32_dpp v163, v167 row_ror:8 row_mask:0xf bank_mask:0x3
	global_store_dwordx4 v[168:169], v[156:159], off nt
	global_store_dwordx4 v[170:171], v[160:163], off nt
; __device__ __forceinline__ unsigned pack2(float a, float b) { return (unsigned)f2bf(a) | ((unsigned)f2bf(b) << 16); }
; __device__ __forceinline__ void phase_gemm_in(const Params& p, char* smem) {
;     ...
; #pragma unroll
;     for (int i = 0; i < 8; ++i) {
;       const int m = mt * 256 + wm * 128 + i * 16 + (lane & 15);
; #pragma unroll
;       for (int j = 0; j < 4; ++j) {
;         const int n = ncol0 + wn * 64 + j * 16 + (lane >> 4) * 4;
;         uint2 o;
;         o.x = pack2(acc[i][j][0], acc[i][j][1]);
;         o.y = pack2(acc[i][j][2], acc[i][j][3]);
;         *(uint2*)(dst + (size_t)m * ldd + n) = o;
;       }
;     }
	v_or_b32_e32 v172, 0x20, v2
	v_mad_i64_i32 v[132:133], s[26:27], s14, v172, 0
	v_lshl_add_u64 v[132:133], v[132:133], 1, s[12:13]
	v_lshl_add_u64 v[132:133], v[132:133], 0, v[0:1]
	v_lshl_add_u64 v[134:135], v[132:133], 0, s[18:19]
	v_cvt_pk_bf16_f32 v144, v96, v97
	v_cvt_pk_bf16_f32 v146, v92, v93
	v_cvt_pk_bf16_f32 v145, v98, v99
	v_cvt_pk_bf16_f32 v147, v94, v95
	v_cvt_pk_bf16_f32 v148, v88, v89
	v_cvt_pk_bf16_f32 v150, v84, v85
	v_cvt_pk_bf16_f32 v149, v90, v91
	v_cvt_pk_bf16_f32 v151, v86, v87
	v_permlane16_swap_b32_e32 v144, v146
	v_permlane16_swap_b32_e32 v145, v147
	v_permlane16_swap_b32_e32 v148, v150
	v_permlane16_swap_b32_e32 v149, v151
	v_mov_b32_e32 v152, v144
	v_mov_b32_e32 v153, v145
	v_mov_b32_e32 v154, v146
	v_mov_b32_e32 v155, v147
	v_mov_b32_dpp v144, v148 row_ror:8 row_mask:0xf bank_mask:0xc
	v_mov_b32_dpp v145, v149 row_ror:8 row_mask:0xf bank_mask:0xc
	v_mov_b32_dpp v146, v150 row_ror:8 row_mask:0xf bank_mask:0xc
	v_mov_b32_dpp v147, v151 row_ror:8 row_mask:0xf bank_mask:0xc
	v_mov_b32_dpp v148, v152 row_ror:8 row_mask:0xf bank_mask:0x3
	v_mov_b32_dpp v149, v153 row_ror:8 row_mask:0xf bank_mask:0x3
	v_mov_b32_dpp v150, v154 row_ror:8 row_mask:0xf bank_mask:0x3
	v_mov_b32_dpp v151, v155 row_ror:8 row_mask:0xf bank_mask:0x3
	global_store_dwordx4 v[132:133], v[144:147], off nt
	global_store_dwordx4 v[134:135], v[148:151], off nt
	v_or_b32_e32 v172, 0x30, v2
	v_mad_i64_i32 v[168:169], s[26:27], s14, v172, 0
	v_lshl_add_u64 v[168:169], v[168:169], 1, s[12:13]
	v_lshl_add_u64 v[168:169], v[168:169], 0, v[0:1]
	v_lshl_add_u64 v[170:171], v[168:169], 0, s[18:19]
	v_cvt_pk_bf16_f32 v156, v80, v81
	v_cvt_pk_bf16_f32 v158, v76, v77
	v_cvt_pk_bf16_f32 v157, v82, v83
	v_cvt_pk_bf16_f32 v159, v78, v79
	v_cvt_pk_bf16_f32 v160, v72, v73
	v_cvt_pk_bf16_f32 v162, v68, v69
	v_cvt_pk_bf16_f32 v161, v74, v75
	v_cvt_pk_bf16_f32 v163, v70, v71
	v_permlane16_swap_b32_e32 v156, v158
	v_permlane16_swap_b32_e32 v157, v159
	v_permlane16_swap_b32_e32 v160, v162
	v_permlane16_swap_b32_e32 v161, v163
	v_mov_b32_e32 v164, v156
	v_mov_b32_e32 v165, v157
	v_mov_b32_e32 v166, v158
	v_mov_b32_e32 v167, v159
	v_mov_b32_dpp v156, v160 row_ror:8 row_mask:0xf bank_mask:0xc
	v_mov_b32_dpp v157, v161 row_ror:8 row_mask:0xf bank_mask:0xc
	v_mov_b32_dpp v158, v162 row_ror:8 row_mask:0xf bank_mask:0xc
	v_mov_b32_dpp v159, v163 row_ror:8 row_mask:0xf bank_mask:0xc
	v_mov_b32_dpp v160, v164 row_ror:8 row_mask:0xf bank_mask:0x3
	v_mov_b32_dpp v161, v165 row_ror:8 row_mask:0xf bank_mask:0x3
	v_mov_b32_dpp v162, v166 row_ror:8 row_mask:0xf bank_mask:0x3
	v_mov_b32_dpp v163, v167 row_ror:8 row_mask:0xf bank_mask:0x3
	global_store_dwordx4 v[168:169], v[156:159], off nt
	global_store_dwordx4 v[170:171], v[160:163], off nt
	v_or_b32_e32 v172, 0x40, v2
	v_mad_i64_i32 v[132:133], s[26:27], s14, v172, 0
	v_lshl_add_u64 v[132:133], v[132:133], 1, s[12:13]
	v_lshl_add_u64 v[132:133], v[132:133], 0, v[0:1]
	v_lshl_add_u64 v[134:135], v[132:133], 0, s[18:19]
	v_cvt_pk_bf16_f32 v144, v64, v65
	v_cvt_pk_bf16_f32 v146, v60, v61
	v_cvt_pk_bf16_f32 v145, v66, v67
	v_cvt_pk_bf16_f32 v147, v62, v63
	v_cvt_pk_bf16_f32 v148, v56, v57
	v_cvt_pk_bf16_f32 v150, v52, v53
	v_cvt_pk_bf16_f32 v149, v58, v59
	v_cvt_pk_bf16_f32 v151, v54, v55
	v_permlane16_swap_b32_e32 v144, v146
	v_permlane16_swap_b32_e32 v145, v147
	v_permlane16_swap_b32_e32 v148, v150
	v_permlane16_swap_b32_e32 v149, v151
	v_mov_b32_e32 v152, v144
	v_mov_b32_e32 v153, v145
	v_mov_b32_e32 v154, v146
	v_mov_b32_e32 v155, v147
	v_mov_b32_dpp v144, v148 row_ror:8 row_mask:0xf bank_mask:0xc
	v_mov_b32_dpp v145, v149 row_ror:8 row_mask:0xf bank_mask:0xc
	v_mov_b32_dpp v146, v150 row_ror:8 row_mask:0xf bank_mask:0xc
	v_mov_b32_dpp v147, v151 row_ror:8 row_mask:0xf bank_mask:0xc
	v_mov_b32_dpp v148, v152 row_ror:8 row_mask:0xf bank_mask:0x3
	v_mov_b32_dpp v149, v153 row_ror:8 row_mask:0xf bank_mask:0x3
	v_mov_b32_dpp v150, v154 row_ror:8 row_mask:0xf bank_mask:0x3
	v_mov_b32_dpp v151, v155 row_ror:8 row_mask:0xf bank_mask:0x3
	global_store_dwordx4 v[132:133], v[144:147], off nt
	global_store_dwordx4 v[134:135], v[148:151], off nt
	v_or_b32_e32 v172, 0x50, v2
	v_mad_i64_i32 v[168:169], s[26:27], s14, v172, 0
; __device__ __forceinline__ unsigned pack2(float a, float b) { return (unsigned)f2bf(a) | ((unsigned)f2bf(b) << 16); }
; __device__ __forceinline__ void phase_gemm_in(const Params& p, char* smem) {
;     ...
; #pragma unroll
;     for (int i = 0; i < 8; ++i) {
;       const int m = mt * 256 + wm * 128 + i * 16 + (lane & 15);
; #pragma unroll
;       for (int j = 0; j < 4; ++j) {
;         const int n = ncol0 + wn * 64 + j * 16 + (lane >> 4) * 4;
;         uint2 o;
;         o.x = pack2(acc[i][j][0], acc[i][j][1]);
;         o.y = pack2(acc[i][j][2], acc[i][j][3]);
;         *(uint2*)(dst + (size_t)m * ldd + n) = o;
;       }
;     }
	v_lshl_add_u64 v[168:169], v[168:169], 1, s[12:13]
	v_lshl_add_u64 v[168:169], v[168:169], 0, v[0:1]
	v_lshl_add_u64 v[170:171], v[168:169], 0, s[18:19]
	v_cvt_pk_bf16_f32 v156, v48, v49
	v_cvt_pk_bf16_f32 v158, v44, v45
	v_cvt_pk_bf16_f32 v157, v50, v51
	v_cvt_pk_bf16_f32 v159, v46, v47
	v_cvt_pk_bf16_f32 v160, v40, v41
	v_cvt_pk_bf16_f32 v162, v36, v37
	v_cvt_pk_bf16_f32 v161, v42, v43
	v_cvt_pk_bf16_f32 v163, v38, v39
	v_permlane16_swap_b32_e32 v156, v158
	v_permlane16_swap_b32_e32 v157, v159
	v_permlane16_swap_b32_e32 v160, v162
	v_permlane16_swap_b32_e32 v161, v163
	v_mov_b32_e32 v164, v156
	v_mov_b32_e32 v165, v157
	v_mov_b32_e32 v166, v158
	v_mov_b32_e32 v167, v159
	v_mov_b32_dpp v156, v160 row_ror:8 row_mask:0xf bank_mask:0xc
	v_mov_b32_dpp v157, v161 row_ror:8 row_mask:0xf bank_mask:0xc
	v_mov_b32_dpp v158, v162 row_ror:8 row_mask:0xf bank_mask:0xc
	v_mov_b32_dpp v159, v163 row_ror:8 row_mask:0xf bank_mask:0xc
	v_mov_b32_dpp v160, v164 row_ror:8 row_mask:0xf bank_mask:0x3
	v_mov_b32_dpp v161, v165 row_ror:8 row_mask:0xf bank_mask:0x3
	v_mov_b32_dpp v162, v166 row_ror:8 row_mask:0xf bank_mask:0x3
	v_mov_b32_dpp v163, v167 row_ror:8 row_mask:0xf bank_mask:0x3
	global_store_dwordx4 v[168:169], v[156:159], off nt
	global_store_dwordx4 v[170:171], v[160:163], off nt
	v_or_b32_e32 v172, 0x60, v2
	v_mad_i64_i32 v[132:133], s[26:27], s14, v172, 0
	v_lshl_add_u64 v[132:133], v[132:133], 1, s[12:13]
	v_lshl_add_u64 v[132:133], v[132:133], 0, v[0:1]
	v_lshl_add_u64 v[134:135], v[132:133], 0, s[18:19]
	v_cvt_pk_bf16_f32 v144, v32, v33
	v_cvt_pk_bf16_f32 v146, v24, v25
	v_cvt_pk_bf16_f32 v145, v34, v35
	v_cvt_pk_bf16_f32 v147, v26, v27
	v_cvt_pk_bf16_f32 v148, v20, v21
	v_cvt_pk_bf16_f32 v150, v16, v17
	v_cvt_pk_bf16_f32 v149, v22, v23
	v_cvt_pk_bf16_f32 v151, v18, v19
	v_permlane16_swap_b32_e32 v144, v146
	v_permlane16_swap_b32_e32 v145, v147
	v_permlane16_swap_b32_e32 v148, v150
	v_permlane16_swap_b32_e32 v149, v151
	v_mov_b32_e32 v152, v144
	v_mov_b32_e32 v153, v145
	v_mov_b32_e32 v154, v146
	v_mov_b32_e32 v155, v147
	v_mov_b32_dpp v144, v148 row_ror:8 row_mask:0xf bank_mask:0xc
	v_mov_b32_dpp v145, v149 row_ror:8 row_mask:0xf bank_mask:0xc
	v_mov_b32_dpp v146, v150 row_ror:8 row_mask:0xf bank_mask:0xc
	v_mov_b32_dpp v147, v151 row_ror:8 row_mask:0xf bank_mask:0xc
	v_mov_b32_dpp v148, v152 row_ror:8 row_mask:0xf bank_mask:0x3
	v_mov_b32_dpp v149, v153 row_ror:8 row_mask:0xf bank_mask:0x3
	v_mov_b32_dpp v150, v154 row_ror:8 row_mask:0xf bank_mask:0x3
	v_mov_b32_dpp v151, v155 row_ror:8 row_mask:0xf bank_mask:0x3
	global_store_dwordx4 v[132:133], v[144:147], off nt
	global_store_dwordx4 v[134:135], v[148:151], off nt
	v_or_b32_e32 v172, 0x70, v2
	v_mad_i64_i32 v[168:169], s[26:27], s14, v172, 0
	v_lshl_add_u64 v[168:169], v[168:169], 1, s[12:13]
	v_lshl_add_u64 v[168:169], v[168:169], 0, v[0:1]
	v_lshl_add_u64 v[170:171], v[168:169], 0, s[18:19]
	v_cvt_pk_bf16_f32 v156, v12, v13
	v_cvt_pk_bf16_f32 v158, v8, v9
	v_cvt_pk_bf16_f32 v157, v14, v15
	v_cvt_pk_bf16_f32 v159, v10, v11
	v_cvt_pk_bf16_f32 v160, v4, v5
	v_cvt_pk_bf16_f32 v162, v28, v29
	v_cvt_pk_bf16_f32 v161, v6, v7
	v_cvt_pk_bf16_f32 v163, v30, v31
	v_permlane16_swap_b32_e32 v156, v158
	v_permlane16_swap_b32_e32 v157, v159
	v_permlane16_swap_b32_e32 v160, v162
	v_permlane16_swap_b32_e32 v161, v163
	v_mov_b32_e32 v164, v156
	v_mov_b32_e32 v165, v157
	v_mov_b32_e32 v166, v158
	v_mov_b32_e32 v167, v159
	v_mov_b32_dpp v156, v160 row_ror:8 row_mask:0xf bank_mask:0xc
	v_mov_b32_dpp v157, v161 row_ror:8 row_mask:0xf bank_mask:0xc
	v_mov_b32_dpp v158, v162 row_ror:8 row_mask:0xf bank_mask:0xc
	v_mov_b32_dpp v159, v163 row_ror:8 row_mask:0xf bank_mask:0xc
	v_mov_b32_dpp v160, v164 row_ror:8 row_mask:0xf bank_mask:0x3
	v_mov_b32_dpp v161, v165 row_ror:8 row_mask:0xf bank_mask:0x3
	v_mov_b32_dpp v162, v166 row_ror:8 row_mask:0xf bank_mask:0x3
	v_mov_b32_dpp v163, v167 row_ror:8 row_mask:0xf bank_mask:0x3
	global_store_dwordx4 v[168:169], v[156:159], off nt
	global_store_dwordx4 v[170:171], v[160:163], off nt
	s_add_i32 s23, s23, 1
	s_cmp_eq_u32 s23, s17
	s_cselect_b64 s[12:13], -1, 0
	s_mov_b32 s31, 0x18000
	s_branch .LBB0_708
